# P4 wkv7 scan rewritten: 4 compute waves (2 state rows per lane, row-pair packed v_pk f32) + 4 helper waves staging/reducing via double-buffered LDS, 1 barrier per 16 steps
# speedup vs baseline: 1.0286x; 1.0286x over previous
; #define SC_LOAD(tc) do { const size_t o_ = base + (size_t)(tc) * 1024 + q * 4; ld_dec = *(const f32x4*)(DEC + o_); ld_kk = *(const u32x2*)(KKn + o_); ld_bb = *(const u32x2*)(BB + o_); \
;             ld_kp = *(const u32x2*)(KP + o_); ld_rr = *(const u32x2*)(RR + o_); ld_vv = *(const unsigned*)(VV + base + (size_t)(tc) * 1024 + half * 32 + q * 2); } while (0)
; #define SC_LD(W, A, Bv, K, R, V, s_) do { const float* p_ = B_ + (s_) * 64 + kl * 4; W = *(const f32x4*)p_; A = *(const f32x4*)(p_ + 2048); Bv = *(const f32x4*)(p_ + 4096); K = *(const f32x4*)(p_ + 6144); R = *(const f32x4*)(p_ + 8192); V = B_[10240 + (s_) * 32 + row]; } while (0)
; __global__ void __launch_bounds__(NT, 2) mk_fwd(Args args) {
;     ...
;         for (int task_ = bx; task_ < 256 * RMUL(4); task_ += G) {
;             const int tb_ = task_ & 255; const int task = ((tb_ >> 4) << 4) | ((tb_ & 7) << 1) | ((tb_ >> 3) & 1); const int bh = task >> 1, half = task & 1, b = bh >> 4, h = bh & 15;
;             const int stp = tid >> 4, q = tid & 15;
;             const size_t base = ((size_t)b * SEQ + stp) * 1024 + h * 64;
;             f32x4 ld_dec; u32x2 ld_kk, ld_bb, ld_kp, ld_rr; unsigned ld_vv;
;     ...
;             __syncthreads();
;             SC_LOAD(0); SC_STORE();
;             __syncthreads();
;             f32x4 S = (f32x4){0.f, 0.f, 0.f, 0.f};
;             const int row = wave * 4 + (lane >> 4), kl = lane & 15;
;             const float* B_ = (const float*)lds;
;             for (int c = 0; c < SEQ / TC; ++c) {
;                 if (c + 1 < SEQ / TC) SC_LOAD((c + 1) * TC);
;     ...
;                 f32x4 w0, a0, b0, k0, r0, w1, a1, b1, k1, r1; float v0, v1;
;                 SC_LD(w0, a0, b0, k0, r0, v0, 0);
; #pragma unroll
;                 for (int s = 0; s < TC; s += 2) {
;                     SC_LD(w1, a1, b1, k1, r1, v1, s + 1);
;                     SC_STEP(w0, a0, b0, k0, r0, v0, s);
;                     if (s + 2 < TC) SC_LD(w0, a0, b0, k0, r0, v0, s + 2);
;                     SC_STEP(w1, a1, b1, k1, r1, v1, s + 1);
.LBB0_443:
	s_cmp_lt_i32 s94, 5
	s_cselect_b64 s[6:7], -1, 0
	s_and_b64 s[0:1], s[6:7], s[0:1]
	s_and_b64 s[6:7], s[0:1], s[38:39]
	s_andn2_b64 vcc, exec, s[6:7]
	s_cbranch_vccnz .LBB0_452
	s_mov_b32 s48, s2
.Lp4_task:
	s_and_b32 s3, s48, 0xf0
	s_and_b32 s6, s48, 7
	s_lshl_b32 s6, s6, 1
	s_or_b32 s3, s3, s6
	s_bfe_u32 s6, s48, 0x10003
	s_or_b32 s3, s3, s6
	s_and_b32 s33, s3, 1
	s_lshr_b32 s6, s3, 1
	s_and_b32 s7, s6, 15
	s_lshr_b32 s6, s6, 4
	s_lshl_b32 s6, s6, 21
	s_lshl_b32 s7, s7, 6
	s_or_b32 s6, s6, s7
	s_lshl_b32 s7, s6, 1
	s_lshl_b32 s8, s6, 2
	s_add_u32 s38, s90, s8
	s_addc_u32 s39, s91, 0
	s_add_u32 s40, s30, s7
	s_addc_u32 s41, s31, 0
	s_add_u32 s42, s34, s7
	s_addc_u32 s43, s35, 0
	s_add_u32 s44, s96, s7
	s_addc_u32 s45, s97, 0
	s_add_u32 s46, s28, s7
	s_addc_u32 s47, s29, 0
	s_lshl_b32 s9, s33, 6
	s_add_u32 s9, s9, s7
	s_add_u32 s52, s24, s9
	s_addc_u32 s53, s25, 0
	s_lshl_b32 s9, s33, 7
	s_add_u32 s9, s9, s8
	s_add_u32 s54, s20, s9
	s_addc_u32 s55, s21, 0
	s_waitcnt vmcnt(0) lgkmcnt(0)
	s_barrier
	s_cmp_gt_u32 s85, 3
	s_cbranch_scc1 .Lp4_helper
	v_and_b32_e32 v54, 15, v128
	v_lshrrev_b32_e32 v55, 4, v128
	v_lshl_or_b32 v55, s85, 2, v55
	v_lshlrev_b32_e32 v80, 4, v54
	v_lshlrev_b32_e32 v81, 3, v55
	v_add_u32_e32 v81, 0x5000, v81
	v_mul_u32_u24_e32 v82, 0x90, v55
	v_lshl_add_u32 v82, v54, 3, v82
	v_add_u32_e32 v82, 0xb000, v82
	v_mov_b32_e32 v72, 0
	v_mov_b32_e32 v73, 0
	v_mov_b32_e32 v74, 0
	v_mov_b32_e32 v75, 0
	v_mov_b32_e32 v76, 0
	v_mov_b32_e32 v77, 0
	v_mov_b32_e32 v78, 0
	v_mov_b32_e32 v79, 0
	s_movk_i32 s10, 0x80
	s_barrier
.Lp4_cchunk:
	ds_read_b128 v[86:89], v80 offset:4096
	ds_read_b128 v[90:93], v80 offset:0
	ds_read_b128 v[94:97], v80 offset:12288
	ds_read_b64 v[68:69], v81 offset:0
	ds_read_b128 v[98:101], v80 offset:8192
	ds_read_b128 v[102:105], v80 offset:16384
	ds_read_b128 v[108:111], v80 offset:4352
	ds_read_b128 v[112:115], v80 offset:256
	ds_read_b128 v[116:119], v80 offset:12544
	ds_read_b64 v[66:67], v81 offset:128
	ds_read_b128 v[120:123], v80 offset:8448
	s_waitcnt lgkmcnt(6)
	v_pk_mul_f32 v[62:63], v[72:73], v[86:87] op_sel_hi:[1,0]
	v_pk_mul_f32 v[54:55], v[72:73], v[90:91] op_sel_hi:[1,0]
	v_pk_fma_f32 v[62:63], v[74:75], v[86:87], v[62:63] op_sel:[0,1,0] op_sel_hi:[1,1,1]
	v_pk_mul_f32 v[56:57], v[74:75], v[90:91] op_sel:[0,1] op_sel_hi:[1,1]
	v_pk_fma_f32 v[62:63], v[76:77], v[88:89], v[62:63] op_sel_hi:[1,0,1]
	v_pk_mul_f32 v[58:59], v[76:77], v[92:93] op_sel_hi:[1,0]
	v_pk_fma_f32 v[62:63], v[78:79], v[88:89], v[62:63] op_sel:[0,1,0] op_sel_hi:[1,1,1]
	v_pk_mul_f32 v[60:61], v[78:79], v[92:93] op_sel:[0,1] op_sel_hi:[1,1]
	ds_read_b128 v[124:127], v80 offset:16640
	v_add_f32_dpp v62, v62, v62 quad_perm:[1,0,3,2] row_mask:0xf bank_mask:0xf bound_ctrl:1
	v_add_f32_dpp v63, v63, v63 quad_perm:[1,0,3,2] row_mask:0xf bank_mask:0xf bound_ctrl:1
	v_pk_fma_f32 v[54:55], v[68:69], v[94:95], v[54:55] op_sel_hi:[1,0,1]
	v_add_f32_dpp v62, v62, v62 quad_perm:[2,3,0,1] row_mask:0xf bank_mask:0xf bound_ctrl:1
	v_add_f32_dpp v63, v63, v63 quad_perm:[2,3,0,1] row_mask:0xf bank_mask:0xf bound_ctrl:1
	v_pk_fma_f32 v[56:57], v[68:69], v[94:95], v[56:57] op_sel:[0,1,0] op_sel_hi:[1,1,1]
	v_add_f32_dpp v62, v62, v62 row_half_mirror row_mask:0xf bank_mask:0xf bound_ctrl:1
	v_add_f32_dpp v63, v63, v63 row_half_mirror row_mask:0xf bank_mask:0xf bound_ctrl:1
	v_pk_fma_f32 v[58:59], v[68:69], v[96:97], v[58:59] op_sel_hi:[1,0,1]
	v_add_f32_dpp v62, v62, v62 row_mirror row_mask:0xf bank_mask:0xf bound_ctrl:1
	v_add_f32_dpp v63, v63, v63 row_mirror row_mask:0xf bank_mask:0xf bound_ctrl:1
	v_pk_fma_f32 v[60:61], v[68:69], v[96:97], v[60:61] op_sel:[0,1,0] op_sel_hi:[1,1,1]
	v_pk_fma_f32 v[72:73], v[62:63], v[98:99], v[54:55] op_sel_hi:[1,0,1]
	v_pk_fma_f32 v[74:75], v[62:63], v[98:99], v[56:57] op_sel:[0,1,0] op_sel_hi:[1,1,1]
	v_pk_fma_f32 v[76:77], v[62:63], v[100:101], v[58:59] op_sel_hi:[1,0,1]
	v_pk_fma_f32 v[78:79], v[62:63], v[100:101], v[60:61] op_sel:[0,1,0] op_sel_hi:[1,1,1]
	ds_read_b128 v[86:89], v80 offset:4608
	ds_read_b128 v[90:93], v80 offset:512
	ds_read_b128 v[94:97], v80 offset:12800
	ds_read_b64 v[68:69], v81 offset:256
	ds_read_b128 v[98:101], v80 offset:8704
	s_waitcnt lgkmcnt(6)
	v_pk_mul_f32 v[62:63], v[72:73], v[108:109] op_sel_hi:[1,0]
	v_pk_mul_f32 v[64:65], v[72:73], v[102:103] op_sel_hi:[1,0]
	v_pk_mul_f32 v[54:55], v[72:73], v[112:113] op_sel_hi:[1,0]
	v_pk_fma_f32 v[62:63], v[74:75], v[108:109], v[62:63] op_sel:[0,1,0] op_sel_hi:[1,1,1]
	v_pk_fma_f32 v[64:65], v[74:75], v[102:103], v[64:65] op_sel:[0,1,0] op_sel_hi:[1,1,1]
	v_pk_mul_f32 v[56:57], v[74:75], v[112:113] op_sel:[0,1] op_sel_hi:[1,1]
	v_pk_fma_f32 v[62:63], v[76:77], v[110:111], v[62:63] op_sel_hi:[1,0,1]
	v_pk_fma_f32 v[64:65], v[76:77], v[104:105], v[64:65] op_sel_hi:[1,0,1]
	v_pk_mul_f32 v[58:59], v[76:77], v[114:115] op_sel_hi:[1,0]
	v_pk_fma_f32 v[62:63], v[78:79], v[110:111], v[62:63] op_sel:[0,1,0] op_sel_hi:[1,1,1]
	v_pk_fma_f32 v[64:65], v[78:79], v[104:105], v[64:65] op_sel:[0,1,0] op_sel_hi:[1,1,1]
	v_pk_mul_f32 v[60:61], v[78:79], v[114:115] op_sel:[0,1] op_sel_hi:[1,1]
	ds_write_b64 v82, v[64:65] offset:0
	ds_read_b128 v[102:105], v80 offset:16896
	v_add_f32_dpp v62, v62, v62 quad_perm:[1,0,3,2] row_mask:0xf bank_mask:0xf bound_ctrl:1
	v_add_f32_dpp v63, v63, v63 quad_perm:[1,0,3,2] row_mask:0xf bank_mask:0xf bound_ctrl:1
	v_pk_fma_f32 v[54:55], v[66:67], v[116:117], v[54:55] op_sel_hi:[1,0,1]
	v_add_f32_dpp v62, v62, v62 quad_perm:[2,3,0,1] row_mask:0xf bank_mask:0xf bound_ctrl:1
	v_add_f32_dpp v63, v63, v63 quad_perm:[2,3,0,1] row_mask:0xf bank_mask:0xf bound_ctrl:1
	v_pk_fma_f32 v[56:57], v[66:67], v[116:117], v[56:57] op_sel:[0,1,0] op_sel_hi:[1,1,1]
	v_add_f32_dpp v62, v62, v62 row_half_mirror row_mask:0xf bank_mask:0xf bound_ctrl:1
	v_add_f32_dpp v63, v63, v63 row_half_mirror row_mask:0xf bank_mask:0xf bound_ctrl:1
	v_pk_fma_f32 v[58:59], v[66:67], v[118:119], v[58:59] op_sel_hi:[1,0,1]
	v_add_f32_dpp v62, v62, v62 row_mirror row_mask:0xf bank_mask:0xf bound_ctrl:1
	v_add_f32_dpp v63, v63, v63 row_mirror row_mask:0xf bank_mask:0xf bound_ctrl:1
	v_pk_fma_f32 v[60:61], v[66:67], v[118:119], v[60:61] op_sel:[0,1,0] op_sel_hi:[1,1,1]
	v_pk_fma_f32 v[72:73], v[62:63], v[120:121], v[54:55] op_sel_hi:[1,0,1]
	v_pk_fma_f32 v[74:75], v[62:63], v[120:121], v[56:57] op_sel:[0,1,0] op_sel_hi:[1,1,1]
	v_pk_fma_f32 v[76:77], v[62:63], v[122:123], v[58:59] op_sel_hi:[1,0,1]
	v_pk_fma_f32 v[78:79], v[62:63], v[122:123], v[60:61] op_sel:[0,1,0] op_sel_hi:[1,1,1]
	ds_read_b128 v[108:111], v80 offset:4864
	ds_read_b128 v[112:115], v80 offset:768
	ds_read_b128 v[116:119], v80 offset:13056
	ds_read_b64 v[66:67], v81 offset:384
	ds_read_b128 v[120:123], v80 offset:8960
	s_waitcnt lgkmcnt(7)
; #define SC_LD(W, A, Bv, K, R, V, s_) do { const float* p_ = B_ + (s_) * 64 + kl * 4; W = *(const f32x4*)p_; A = *(const f32x4*)(p_ + 2048); Bv = *(const f32x4*)(p_ + 4096); K = *(const f32x4*)(p_ + 6144); R = *(const f32x4*)(p_ + 8192); V = B_[10240 + (s_) * 32 + row]; } while (0)
; #define SC_STEP(W, A, Bv, K, R, V, s_) do { float sa_ = S.x * A.x; sa_ = fmaf(S.y, A.y, sa_); sa_ = fmaf(S.z, A.z, sa_); sa_ = fmaf(S.w, A.w, sa_); \
;                     sa_ = row16_sum(sa_); S = S * W + Bv * sa_ + K * V; \
;                     float y_ = S.x * R.x; y_ = fmaf(S.y, R.y, y_); y_ = fmaf(S.z, R.z, y_); y_ = fmaf(S.w, R.w, y_); yp[((s_) * 32 + row) * 20 + kl] = y_; } while (0)
; __global__ void __launch_bounds__(NT, 2) mk_fwd(Args args) {
;     ...
;                 f32x4 w0, a0, b0, k0, r0, w1, a1, b1, k1, r1; float v0, v1;
;                 SC_LD(w0, a0, b0, k0, r0, v0, 0);
; #pragma unroll
;                 for (int s = 0; s < TC; s += 2) {
;                     SC_LD(w1, a1, b1, k1, r1, v1, s + 1);
;                     SC_STEP(w0, a0, b0, k0, r0, v0, s);
;                     if (s + 2 < TC) SC_LD(w0, a0, b0, k0, r0, v0, s + 2);
;                     SC_STEP(w1, a1, b1, k1, r1, v1, s + 1);
	v_pk_mul_f32 v[62:63], v[72:73], v[86:87] op_sel_hi:[1,0]
	v_pk_mul_f32 v[64:65], v[72:73], v[124:125] op_sel_hi:[1,0]
	v_pk_mul_f32 v[54:55], v[72:73], v[90:91] op_sel_hi:[1,0]
	v_pk_fma_f32 v[62:63], v[74:75], v[86:87], v[62:63] op_sel:[0,1,0] op_sel_hi:[1,1,1]
	v_pk_fma_f32 v[64:65], v[74:75], v[124:125], v[64:65] op_sel:[0,1,0] op_sel_hi:[1,1,1]
	v_pk_mul_f32 v[56:57], v[74:75], v[90:91] op_sel:[0,1] op_sel_hi:[1,1]
	v_pk_fma_f32 v[62:63], v[76:77], v[88:89], v[62:63] op_sel_hi:[1,0,1]
	v_pk_fma_f32 v[64:65], v[76:77], v[126:127], v[64:65] op_sel_hi:[1,0,1]
	v_pk_mul_f32 v[58:59], v[76:77], v[92:93] op_sel_hi:[1,0]
	v_pk_fma_f32 v[62:63], v[78:79], v[88:89], v[62:63] op_sel:[0,1,0] op_sel_hi:[1,1,1]
	v_pk_fma_f32 v[64:65], v[78:79], v[126:127], v[64:65] op_sel:[0,1,0] op_sel_hi:[1,1,1]
	v_pk_mul_f32 v[60:61], v[78:79], v[92:93] op_sel:[0,1] op_sel_hi:[1,1]
	ds_write_b64 v82, v[64:65] offset:2304
	ds_read_b128 v[124:127], v80 offset:17152
	v_add_f32_dpp v62, v62, v62 quad_perm:[1,0,3,2] row_mask:0xf bank_mask:0xf bound_ctrl:1
	v_add_f32_dpp v63, v63, v63 quad_perm:[1,0,3,2] row_mask:0xf bank_mask:0xf bound_ctrl:1
	v_pk_fma_f32 v[54:55], v[68:69], v[94:95], v[54:55] op_sel_hi:[1,0,1]
	v_add_f32_dpp v62, v62, v62 quad_perm:[2,3,0,1] row_mask:0xf bank_mask:0xf bound_ctrl:1
	v_add_f32_dpp v63, v63, v63 quad_perm:[2,3,0,1] row_mask:0xf bank_mask:0xf bound_ctrl:1
	v_pk_fma_f32 v[56:57], v[68:69], v[94:95], v[56:57] op_sel:[0,1,0] op_sel_hi:[1,1,1]
	v_add_f32_dpp v62, v62, v62 row_half_mirror row_mask:0xf bank_mask:0xf bound_ctrl:1
	v_add_f32_dpp v63, v63, v63 row_half_mirror row_mask:0xf bank_mask:0xf bound_ctrl:1
	v_pk_fma_f32 v[58:59], v[68:69], v[96:97], v[58:59] op_sel_hi:[1,0,1]
	v_add_f32_dpp v62, v62, v62 row_mirror row_mask:0xf bank_mask:0xf bound_ctrl:1
	v_add_f32_dpp v63, v63, v63 row_mirror row_mask:0xf bank_mask:0xf bound_ctrl:1
	v_pk_fma_f32 v[60:61], v[68:69], v[96:97], v[60:61] op_sel:[0,1,0] op_sel_hi:[1,1,1]
	v_pk_fma_f32 v[72:73], v[62:63], v[98:99], v[54:55] op_sel_hi:[1,0,1]
	v_pk_fma_f32 v[74:75], v[62:63], v[98:99], v[56:57] op_sel:[0,1,0] op_sel_hi:[1,1,1]
	v_pk_fma_f32 v[76:77], v[62:63], v[100:101], v[58:59] op_sel_hi:[1,0,1]
	v_pk_fma_f32 v[78:79], v[62:63], v[100:101], v[60:61] op_sel:[0,1,0] op_sel_hi:[1,1,1]
	ds_read_b128 v[86:89], v80 offset:5120
	ds_read_b128 v[90:93], v80 offset:1024
	ds_read_b128 v[94:97], v80 offset:13312
	ds_read_b64 v[68:69], v81 offset:512
	ds_read_b128 v[98:101], v80 offset:9216
	s_waitcnt lgkmcnt(7)
	v_pk_mul_f32 v[62:63], v[72:73], v[108:109] op_sel_hi:[1,0]
	v_pk_mul_f32 v[64:65], v[72:73], v[102:103] op_sel_hi:[1,0]
	v_pk_mul_f32 v[54:55], v[72:73], v[112:113] op_sel_hi:[1,0]
	v_pk_fma_f32 v[62:63], v[74:75], v[108:109], v[62:63] op_sel:[0,1,0] op_sel_hi:[1,1,1]
	v_pk_fma_f32 v[64:65], v[74:75], v[102:103], v[64:65] op_sel:[0,1,0] op_sel_hi:[1,1,1]
	v_pk_mul_f32 v[56:57], v[74:75], v[112:113] op_sel:[0,1] op_sel_hi:[1,1]
	v_pk_fma_f32 v[62:63], v[76:77], v[110:111], v[62:63] op_sel_hi:[1,0,1]
	v_pk_fma_f32 v[64:65], v[76:77], v[104:105], v[64:65] op_sel_hi:[1,0,1]
	v_pk_mul_f32 v[58:59], v[76:77], v[114:115] op_sel_hi:[1,0]
	v_pk_fma_f32 v[62:63], v[78:79], v[110:111], v[62:63] op_sel:[0,1,0] op_sel_hi:[1,1,1]
	v_pk_fma_f32 v[64:65], v[78:79], v[104:105], v[64:65] op_sel:[0,1,0] op_sel_hi:[1,1,1]
	v_pk_mul_f32 v[60:61], v[78:79], v[114:115] op_sel:[0,1] op_sel_hi:[1,1]
	ds_write_b64 v82, v[64:65] offset:4608
	ds_read_b128 v[102:105], v80 offset:17408
	v_add_f32_dpp v62, v62, v62 quad_perm:[1,0,3,2] row_mask:0xf bank_mask:0xf bound_ctrl:1
	v_add_f32_dpp v63, v63, v63 quad_perm:[1,0,3,2] row_mask:0xf bank_mask:0xf bound_ctrl:1
	v_pk_fma_f32 v[54:55], v[66:67], v[116:117], v[54:55] op_sel_hi:[1,0,1]
	v_add_f32_dpp v62, v62, v62 quad_perm:[2,3,0,1] row_mask:0xf bank_mask:0xf bound_ctrl:1
	v_add_f32_dpp v63, v63, v63 quad_perm:[2,3,0,1] row_mask:0xf bank_mask:0xf bound_ctrl:1
	v_pk_fma_f32 v[56:57], v[66:67], v[116:117], v[56:57] op_sel:[0,1,0] op_sel_hi:[1,1,1]
	v_add_f32_dpp v62, v62, v62 row_half_mirror row_mask:0xf bank_mask:0xf bound_ctrl:1
	v_add_f32_dpp v63, v63, v63 row_half_mirror row_mask:0xf bank_mask:0xf bound_ctrl:1
	v_pk_fma_f32 v[58:59], v[66:67], v[118:119], v[58:59] op_sel_hi:[1,0,1]
	v_add_f32_dpp v62, v62, v62 row_mirror row_mask:0xf bank_mask:0xf bound_ctrl:1
	v_add_f32_dpp v63, v63, v63 row_mirror row_mask:0xf bank_mask:0xf bound_ctrl:1
	v_pk_fma_f32 v[60:61], v[66:67], v[118:119], v[60:61] op_sel:[0,1,0] op_sel_hi:[1,1,1]
	v_pk_fma_f32 v[72:73], v[62:63], v[120:121], v[54:55] op_sel_hi:[1,0,1]
	v_pk_fma_f32 v[74:75], v[62:63], v[120:121], v[56:57] op_sel:[0,1,0] op_sel_hi:[1,1,1]
	v_pk_fma_f32 v[76:77], v[62:63], v[122:123], v[58:59] op_sel_hi:[1,0,1]
	v_pk_fma_f32 v[78:79], v[62:63], v[122:123], v[60:61] op_sel:[0,1,0] op_sel_hi:[1,1,1]
	ds_read_b128 v[108:111], v80 offset:5376
	ds_read_b128 v[112:115], v80 offset:1280
	ds_read_b128 v[116:119], v80 offset:13568
	ds_read_b64 v[66:67], v81 offset:640
	ds_read_b128 v[120:123], v80 offset:9472
	s_waitcnt lgkmcnt(7)
; #define SC_LD(W, A, Bv, K, R, V, s_) do { const float* p_ = B_ + (s_) * 64 + kl * 4; W = *(const f32x4*)p_; A = *(const f32x4*)(p_ + 2048); Bv = *(const f32x4*)(p_ + 4096); K = *(const f32x4*)(p_ + 6144); R = *(const f32x4*)(p_ + 8192); V = B_[10240 + (s_) * 32 + row]; } while (0)
; #define SC_STEP(W, A, Bv, K, R, V, s_) do { float sa_ = S.x * A.x; sa_ = fmaf(S.y, A.y, sa_); sa_ = fmaf(S.z, A.z, sa_); sa_ = fmaf(S.w, A.w, sa_); \
;                     sa_ = row16_sum(sa_); S = S * W + Bv * sa_ + K * V; \
;                     float y_ = S.x * R.x; y_ = fmaf(S.y, R.y, y_); y_ = fmaf(S.z, R.z, y_); y_ = fmaf(S.w, R.w, y_); yp[((s_) * 32 + row) * 20 + kl] = y_; } while (0)
; __global__ void __launch_bounds__(NT, 2) mk_fwd(Args args) {
;     ...
;                 f32x4 w0, a0, b0, k0, r0, w1, a1, b1, k1, r1; float v0, v1;
;                 SC_LD(w0, a0, b0, k0, r0, v0, 0);
; #pragma unroll
;                 for (int s = 0; s < TC; s += 2) {
;                     SC_LD(w1, a1, b1, k1, r1, v1, s + 1);
;                     SC_STEP(w0, a0, b0, k0, r0, v0, s);
;                     if (s + 2 < TC) SC_LD(w0, a0, b0, k0, r0, v0, s + 2);
;                     SC_STEP(w1, a1, b1, k1, r1, v1, s + 1);
	v_pk_mul_f32 v[62:63], v[72:73], v[86:87] op_sel_hi:[1,0]
	v_pk_mul_f32 v[64:65], v[72:73], v[124:125] op_sel_hi:[1,0]
	v_pk_mul_f32 v[54:55], v[72:73], v[90:91] op_sel_hi:[1,0]
	v_pk_fma_f32 v[62:63], v[74:75], v[86:87], v[62:63] op_sel:[0,1,0] op_sel_hi:[1,1,1]
	v_pk_fma_f32 v[64:65], v[74:75], v[124:125], v[64:65] op_sel:[0,1,0] op_sel_hi:[1,1,1]
	v_pk_mul_f32 v[56:57], v[74:75], v[90:91] op_sel:[0,1] op_sel_hi:[1,1]
	v_pk_fma_f32 v[62:63], v[76:77], v[88:89], v[62:63] op_sel_hi:[1,0,1]
	v_pk_fma_f32 v[64:65], v[76:77], v[126:127], v[64:65] op_sel_hi:[1,0,1]
	v_pk_mul_f32 v[58:59], v[76:77], v[92:93] op_sel_hi:[1,0]
	v_pk_fma_f32 v[62:63], v[78:79], v[88:89], v[62:63] op_sel:[0,1,0] op_sel_hi:[1,1,1]
	v_pk_fma_f32 v[64:65], v[78:79], v[126:127], v[64:65] op_sel:[0,1,0] op_sel_hi:[1,1,1]
	v_pk_mul_f32 v[60:61], v[78:79], v[92:93] op_sel:[0,1] op_sel_hi:[1,1]
	ds_write_b64 v82, v[64:65] offset:6912
	ds_read_b128 v[124:127], v80 offset:17664
	v_add_f32_dpp v62, v62, v62 quad_perm:[1,0,3,2] row_mask:0xf bank_mask:0xf bound_ctrl:1
	v_add_f32_dpp v63, v63, v63 quad_perm:[1,0,3,2] row_mask:0xf bank_mask:0xf bound_ctrl:1
	v_pk_fma_f32 v[54:55], v[68:69], v[94:95], v[54:55] op_sel_hi:[1,0,1]
	v_add_f32_dpp v62, v62, v62 quad_perm:[2,3,0,1] row_mask:0xf bank_mask:0xf bound_ctrl:1
	v_add_f32_dpp v63, v63, v63 quad_perm:[2,3,0,1] row_mask:0xf bank_mask:0xf bound_ctrl:1
	v_pk_fma_f32 v[56:57], v[68:69], v[94:95], v[56:57] op_sel:[0,1,0] op_sel_hi:[1,1,1]
	v_add_f32_dpp v62, v62, v62 row_half_mirror row_mask:0xf bank_mask:0xf bound_ctrl:1
	v_add_f32_dpp v63, v63, v63 row_half_mirror row_mask:0xf bank_mask:0xf bound_ctrl:1
	v_pk_fma_f32 v[58:59], v[68:69], v[96:97], v[58:59] op_sel_hi:[1,0,1]
	v_add_f32_dpp v62, v62, v62 row_mirror row_mask:0xf bank_mask:0xf bound_ctrl:1
	v_add_f32_dpp v63, v63, v63 row_mirror row_mask:0xf bank_mask:0xf bound_ctrl:1
	v_pk_fma_f32 v[60:61], v[68:69], v[96:97], v[60:61] op_sel:[0,1,0] op_sel_hi:[1,1,1]
	v_pk_fma_f32 v[72:73], v[62:63], v[98:99], v[54:55] op_sel_hi:[1,0,1]
	v_pk_fma_f32 v[74:75], v[62:63], v[98:99], v[56:57] op_sel:[0,1,0] op_sel_hi:[1,1,1]
	v_pk_fma_f32 v[76:77], v[62:63], v[100:101], v[58:59] op_sel_hi:[1,0,1]
	v_pk_fma_f32 v[78:79], v[62:63], v[100:101], v[60:61] op_sel:[0,1,0] op_sel_hi:[1,1,1]
	ds_read_b128 v[86:89], v80 offset:5632
	ds_read_b128 v[90:93], v80 offset:1536
	ds_read_b128 v[94:97], v80 offset:13824
	ds_read_b64 v[68:69], v81 offset:768
	ds_read_b128 v[98:101], v80 offset:9728
	s_waitcnt lgkmcnt(7)
	v_pk_mul_f32 v[62:63], v[72:73], v[108:109] op_sel_hi:[1,0]
	v_pk_mul_f32 v[64:65], v[72:73], v[102:103] op_sel_hi:[1,0]
	v_pk_mul_f32 v[54:55], v[72:73], v[112:113] op_sel_hi:[1,0]
	v_pk_fma_f32 v[62:63], v[74:75], v[108:109], v[62:63] op_sel:[0,1,0] op_sel_hi:[1,1,1]
	v_pk_fma_f32 v[64:65], v[74:75], v[102:103], v[64:65] op_sel:[0,1,0] op_sel_hi:[1,1,1]
	v_pk_mul_f32 v[56:57], v[74:75], v[112:113] op_sel:[0,1] op_sel_hi:[1,1]
	v_pk_fma_f32 v[62:63], v[76:77], v[110:111], v[62:63] op_sel_hi:[1,0,1]
	v_pk_fma_f32 v[64:65], v[76:77], v[104:105], v[64:65] op_sel_hi:[1,0,1]
	v_pk_mul_f32 v[58:59], v[76:77], v[114:115] op_sel_hi:[1,0]
	v_pk_fma_f32 v[62:63], v[78:79], v[110:111], v[62:63] op_sel:[0,1,0] op_sel_hi:[1,1,1]
	v_pk_fma_f32 v[64:65], v[78:79], v[104:105], v[64:65] op_sel:[0,1,0] op_sel_hi:[1,1,1]
	v_pk_mul_f32 v[60:61], v[78:79], v[114:115] op_sel:[0,1] op_sel_hi:[1,1]
	ds_write_b64 v82, v[64:65] offset:9216
	ds_read_b128 v[102:105], v80 offset:17920
	v_add_f32_dpp v62, v62, v62 quad_perm:[1,0,3,2] row_mask:0xf bank_mask:0xf bound_ctrl:1
	v_add_f32_dpp v63, v63, v63 quad_perm:[1,0,3,2] row_mask:0xf bank_mask:0xf bound_ctrl:1
	v_pk_fma_f32 v[54:55], v[66:67], v[116:117], v[54:55] op_sel_hi:[1,0,1]
	v_add_f32_dpp v62, v62, v62 quad_perm:[2,3,0,1] row_mask:0xf bank_mask:0xf bound_ctrl:1
	v_add_f32_dpp v63, v63, v63 quad_perm:[2,3,0,1] row_mask:0xf bank_mask:0xf bound_ctrl:1
	v_pk_fma_f32 v[56:57], v[66:67], v[116:117], v[56:57] op_sel:[0,1,0] op_sel_hi:[1,1,1]
	v_add_f32_dpp v62, v62, v62 row_half_mirror row_mask:0xf bank_mask:0xf bound_ctrl:1
	v_add_f32_dpp v63, v63, v63 row_half_mirror row_mask:0xf bank_mask:0xf bound_ctrl:1
	v_pk_fma_f32 v[58:59], v[66:67], v[118:119], v[58:59] op_sel_hi:[1,0,1]
	v_add_f32_dpp v62, v62, v62 row_mirror row_mask:0xf bank_mask:0xf bound_ctrl:1
	v_add_f32_dpp v63, v63, v63 row_mirror row_mask:0xf bank_mask:0xf bound_ctrl:1
	v_pk_fma_f32 v[60:61], v[66:67], v[118:119], v[60:61] op_sel:[0,1,0] op_sel_hi:[1,1,1]
	v_pk_fma_f32 v[72:73], v[62:63], v[120:121], v[54:55] op_sel_hi:[1,0,1]
	v_pk_fma_f32 v[74:75], v[62:63], v[120:121], v[56:57] op_sel:[0,1,0] op_sel_hi:[1,1,1]
	v_pk_fma_f32 v[76:77], v[62:63], v[122:123], v[58:59] op_sel_hi:[1,0,1]
	v_pk_fma_f32 v[78:79], v[62:63], v[122:123], v[60:61] op_sel:[0,1,0] op_sel_hi:[1,1,1]
	ds_read_b128 v[108:111], v80 offset:5888
	ds_read_b128 v[112:115], v80 offset:1792
	ds_read_b128 v[116:119], v80 offset:14080
	ds_read_b64 v[66:67], v81 offset:896
	ds_read_b128 v[120:123], v80 offset:9984
	s_waitcnt lgkmcnt(7)
; #define SC_LD(W, A, Bv, K, R, V, s_) do { const float* p_ = B_ + (s_) * 64 + kl * 4; W = *(const f32x4*)p_; A = *(const f32x4*)(p_ + 2048); Bv = *(const f32x4*)(p_ + 4096); K = *(const f32x4*)(p_ + 6144); R = *(const f32x4*)(p_ + 8192); V = B_[10240 + (s_) * 32 + row]; } while (0)
; #define SC_STEP(W, A, Bv, K, R, V, s_) do { float sa_ = S.x * A.x; sa_ = fmaf(S.y, A.y, sa_); sa_ = fmaf(S.z, A.z, sa_); sa_ = fmaf(S.w, A.w, sa_); \
;                     sa_ = row16_sum(sa_); S = S * W + Bv * sa_ + K * V; \
;                     float y_ = S.x * R.x; y_ = fmaf(S.y, R.y, y_); y_ = fmaf(S.z, R.z, y_); y_ = fmaf(S.w, R.w, y_); yp[((s_) * 32 + row) * 20 + kl] = y_; } while (0)
; __global__ void __launch_bounds__(NT, 2) mk_fwd(Args args) {
;     ...
;                 f32x4 w0, a0, b0, k0, r0, w1, a1, b1, k1, r1; float v0, v1;
;                 SC_LD(w0, a0, b0, k0, r0, v0, 0);
; #pragma unroll
;                 for (int s = 0; s < TC; s += 2) {
;                     SC_LD(w1, a1, b1, k1, r1, v1, s + 1);
;                     SC_STEP(w0, a0, b0, k0, r0, v0, s);
;                     if (s + 2 < TC) SC_LD(w0, a0, b0, k0, r0, v0, s + 2);
;                     SC_STEP(w1, a1, b1, k1, r1, v1, s + 1);
	v_pk_mul_f32 v[62:63], v[72:73], v[86:87] op_sel_hi:[1,0]
	v_pk_mul_f32 v[64:65], v[72:73], v[124:125] op_sel_hi:[1,0]
	v_pk_mul_f32 v[54:55], v[72:73], v[90:91] op_sel_hi:[1,0]
	v_pk_fma_f32 v[62:63], v[74:75], v[86:87], v[62:63] op_sel:[0,1,0] op_sel_hi:[1,1,1]
	v_pk_fma_f32 v[64:65], v[74:75], v[124:125], v[64:65] op_sel:[0,1,0] op_sel_hi:[1,1,1]
	v_pk_mul_f32 v[56:57], v[74:75], v[90:91] op_sel:[0,1] op_sel_hi:[1,1]
	v_pk_fma_f32 v[62:63], v[76:77], v[88:89], v[62:63] op_sel_hi:[1,0,1]
	v_pk_fma_f32 v[64:65], v[76:77], v[126:127], v[64:65] op_sel_hi:[1,0,1]
	v_pk_mul_f32 v[58:59], v[76:77], v[92:93] op_sel_hi:[1,0]
	v_pk_fma_f32 v[62:63], v[78:79], v[88:89], v[62:63] op_sel:[0,1,0] op_sel_hi:[1,1,1]
	v_pk_fma_f32 v[64:65], v[78:79], v[126:127], v[64:65] op_sel:[0,1,0] op_sel_hi:[1,1,1]
	v_pk_mul_f32 v[60:61], v[78:79], v[92:93] op_sel:[0,1] op_sel_hi:[1,1]
	ds_write_b64 v82, v[64:65] offset:11520
	ds_read_b128 v[124:127], v80 offset:18176
	v_add_f32_dpp v62, v62, v62 quad_perm:[1,0,3,2] row_mask:0xf bank_mask:0xf bound_ctrl:1
	v_add_f32_dpp v63, v63, v63 quad_perm:[1,0,3,2] row_mask:0xf bank_mask:0xf bound_ctrl:1
	v_pk_fma_f32 v[54:55], v[68:69], v[94:95], v[54:55] op_sel_hi:[1,0,1]
	v_add_f32_dpp v62, v62, v62 quad_perm:[2,3,0,1] row_mask:0xf bank_mask:0xf bound_ctrl:1
	v_add_f32_dpp v63, v63, v63 quad_perm:[2,3,0,1] row_mask:0xf bank_mask:0xf bound_ctrl:1
	v_pk_fma_f32 v[56:57], v[68:69], v[94:95], v[56:57] op_sel:[0,1,0] op_sel_hi:[1,1,1]
	v_add_f32_dpp v62, v62, v62 row_half_mirror row_mask:0xf bank_mask:0xf bound_ctrl:1
	v_add_f32_dpp v63, v63, v63 row_half_mirror row_mask:0xf bank_mask:0xf bound_ctrl:1
	v_pk_fma_f32 v[58:59], v[68:69], v[96:97], v[58:59] op_sel_hi:[1,0,1]
	v_add_f32_dpp v62, v62, v62 row_mirror row_mask:0xf bank_mask:0xf bound_ctrl:1
	v_add_f32_dpp v63, v63, v63 row_mirror row_mask:0xf bank_mask:0xf bound_ctrl:1
	v_pk_fma_f32 v[60:61], v[68:69], v[96:97], v[60:61] op_sel:[0,1,0] op_sel_hi:[1,1,1]
	v_pk_fma_f32 v[72:73], v[62:63], v[98:99], v[54:55] op_sel_hi:[1,0,1]
	v_pk_fma_f32 v[74:75], v[62:63], v[98:99], v[56:57] op_sel:[0,1,0] op_sel_hi:[1,1,1]
	v_pk_fma_f32 v[76:77], v[62:63], v[100:101], v[58:59] op_sel_hi:[1,0,1]
	v_pk_fma_f32 v[78:79], v[62:63], v[100:101], v[60:61] op_sel:[0,1,0] op_sel_hi:[1,1,1]
	ds_read_b128 v[86:89], v80 offset:6144
	ds_read_b128 v[90:93], v80 offset:2048
	ds_read_b128 v[94:97], v80 offset:14336
	ds_read_b64 v[68:69], v81 offset:1024
	ds_read_b128 v[98:101], v80 offset:10240
	s_waitcnt lgkmcnt(7)
	v_pk_mul_f32 v[62:63], v[72:73], v[108:109] op_sel_hi:[1,0]
	v_pk_mul_f32 v[64:65], v[72:73], v[102:103] op_sel_hi:[1,0]
	v_pk_mul_f32 v[54:55], v[72:73], v[112:113] op_sel_hi:[1,0]
	v_pk_fma_f32 v[62:63], v[74:75], v[108:109], v[62:63] op_sel:[0,1,0] op_sel_hi:[1,1,1]
	v_pk_fma_f32 v[64:65], v[74:75], v[102:103], v[64:65] op_sel:[0,1,0] op_sel_hi:[1,1,1]
	v_pk_mul_f32 v[56:57], v[74:75], v[112:113] op_sel:[0,1] op_sel_hi:[1,1]
	v_pk_fma_f32 v[62:63], v[76:77], v[110:111], v[62:63] op_sel_hi:[1,0,1]
	v_pk_fma_f32 v[64:65], v[76:77], v[104:105], v[64:65] op_sel_hi:[1,0,1]
	v_pk_mul_f32 v[58:59], v[76:77], v[114:115] op_sel_hi:[1,0]
	v_pk_fma_f32 v[62:63], v[78:79], v[110:111], v[62:63] op_sel:[0,1,0] op_sel_hi:[1,1,1]
	v_pk_fma_f32 v[64:65], v[78:79], v[104:105], v[64:65] op_sel:[0,1,0] op_sel_hi:[1,1,1]
	v_pk_mul_f32 v[60:61], v[78:79], v[114:115] op_sel:[0,1] op_sel_hi:[1,1]
	ds_write_b64 v82, v[64:65] offset:13824
	ds_read_b128 v[102:105], v80 offset:18432
	v_add_f32_dpp v62, v62, v62 quad_perm:[1,0,3,2] row_mask:0xf bank_mask:0xf bound_ctrl:1
	v_add_f32_dpp v63, v63, v63 quad_perm:[1,0,3,2] row_mask:0xf bank_mask:0xf bound_ctrl:1
	v_pk_fma_f32 v[54:55], v[66:67], v[116:117], v[54:55] op_sel_hi:[1,0,1]
	v_add_f32_dpp v62, v62, v62 quad_perm:[2,3,0,1] row_mask:0xf bank_mask:0xf bound_ctrl:1
	v_add_f32_dpp v63, v63, v63 quad_perm:[2,3,0,1] row_mask:0xf bank_mask:0xf bound_ctrl:1
	v_pk_fma_f32 v[56:57], v[66:67], v[116:117], v[56:57] op_sel:[0,1,0] op_sel_hi:[1,1,1]
	v_add_f32_dpp v62, v62, v62 row_half_mirror row_mask:0xf bank_mask:0xf bound_ctrl:1
	v_add_f32_dpp v63, v63, v63 row_half_mirror row_mask:0xf bank_mask:0xf bound_ctrl:1
	v_pk_fma_f32 v[58:59], v[66:67], v[118:119], v[58:59] op_sel_hi:[1,0,1]
	v_add_f32_dpp v62, v62, v62 row_mirror row_mask:0xf bank_mask:0xf bound_ctrl:1
	v_add_f32_dpp v63, v63, v63 row_mirror row_mask:0xf bank_mask:0xf bound_ctrl:1
	v_pk_fma_f32 v[60:61], v[66:67], v[118:119], v[60:61] op_sel:[0,1,0] op_sel_hi:[1,1,1]
	v_pk_fma_f32 v[72:73], v[62:63], v[120:121], v[54:55] op_sel_hi:[1,0,1]
	v_pk_fma_f32 v[74:75], v[62:63], v[120:121], v[56:57] op_sel:[0,1,0] op_sel_hi:[1,1,1]
	v_pk_fma_f32 v[76:77], v[62:63], v[122:123], v[58:59] op_sel_hi:[1,0,1]
	v_pk_fma_f32 v[78:79], v[62:63], v[122:123], v[60:61] op_sel:[0,1,0] op_sel_hi:[1,1,1]
	ds_read_b128 v[108:111], v80 offset:6400
	ds_read_b128 v[112:115], v80 offset:2304
	ds_read_b128 v[116:119], v80 offset:14592
	ds_read_b64 v[66:67], v81 offset:1152
	ds_read_b128 v[120:123], v80 offset:10496
	s_waitcnt lgkmcnt(7)
; #define SC_LD(W, A, Bv, K, R, V, s_) do { const float* p_ = B_ + (s_) * 64 + kl * 4; W = *(const f32x4*)p_; A = *(const f32x4*)(p_ + 2048); Bv = *(const f32x4*)(p_ + 4096); K = *(const f32x4*)(p_ + 6144); R = *(const f32x4*)(p_ + 8192); V = B_[10240 + (s_) * 32 + row]; } while (0)
; #define SC_STEP(W, A, Bv, K, R, V, s_) do { float sa_ = S.x * A.x; sa_ = fmaf(S.y, A.y, sa_); sa_ = fmaf(S.z, A.z, sa_); sa_ = fmaf(S.w, A.w, sa_); \
;                     sa_ = row16_sum(sa_); S = S * W + Bv * sa_ + K * V; \
;                     float y_ = S.x * R.x; y_ = fmaf(S.y, R.y, y_); y_ = fmaf(S.z, R.z, y_); y_ = fmaf(S.w, R.w, y_); yp[((s_) * 32 + row) * 20 + kl] = y_; } while (0)
; __global__ void __launch_bounds__(NT, 2) mk_fwd(Args args) {
;     ...
;                 f32x4 w0, a0, b0, k0, r0, w1, a1, b1, k1, r1; float v0, v1;
;                 SC_LD(w0, a0, b0, k0, r0, v0, 0);
; #pragma unroll
;                 for (int s = 0; s < TC; s += 2) {
;                     SC_LD(w1, a1, b1, k1, r1, v1, s + 1);
;                     SC_STEP(w0, a0, b0, k0, r0, v0, s);
;                     if (s + 2 < TC) SC_LD(w0, a0, b0, k0, r0, v0, s + 2);
;                     SC_STEP(w1, a1, b1, k1, r1, v1, s + 1);
	v_pk_mul_f32 v[62:63], v[72:73], v[86:87] op_sel_hi:[1,0]
	v_pk_mul_f32 v[64:65], v[72:73], v[124:125] op_sel_hi:[1,0]
	v_pk_mul_f32 v[54:55], v[72:73], v[90:91] op_sel_hi:[1,0]
	v_pk_fma_f32 v[62:63], v[74:75], v[86:87], v[62:63] op_sel:[0,1,0] op_sel_hi:[1,1,1]
	v_pk_fma_f32 v[64:65], v[74:75], v[124:125], v[64:65] op_sel:[0,1,0] op_sel_hi:[1,1,1]
	v_pk_mul_f32 v[56:57], v[74:75], v[90:91] op_sel:[0,1] op_sel_hi:[1,1]
	v_pk_fma_f32 v[62:63], v[76:77], v[88:89], v[62:63] op_sel_hi:[1,0,1]
	v_pk_fma_f32 v[64:65], v[76:77], v[126:127], v[64:65] op_sel_hi:[1,0,1]
	v_pk_mul_f32 v[58:59], v[76:77], v[92:93] op_sel_hi:[1,0]
	v_pk_fma_f32 v[62:63], v[78:79], v[88:89], v[62:63] op_sel:[0,1,0] op_sel_hi:[1,1,1]
	v_pk_fma_f32 v[64:65], v[78:79], v[126:127], v[64:65] op_sel:[0,1,0] op_sel_hi:[1,1,1]
	v_pk_mul_f32 v[60:61], v[78:79], v[92:93] op_sel:[0,1] op_sel_hi:[1,1]
	ds_write_b64 v82, v[64:65] offset:16128
	ds_read_b128 v[124:127], v80 offset:18688
	v_add_f32_dpp v62, v62, v62 quad_perm:[1,0,3,2] row_mask:0xf bank_mask:0xf bound_ctrl:1
	v_add_f32_dpp v63, v63, v63 quad_perm:[1,0,3,2] row_mask:0xf bank_mask:0xf bound_ctrl:1
	v_pk_fma_f32 v[54:55], v[68:69], v[94:95], v[54:55] op_sel_hi:[1,0,1]
	v_add_f32_dpp v62, v62, v62 quad_perm:[2,3,0,1] row_mask:0xf bank_mask:0xf bound_ctrl:1
	v_add_f32_dpp v63, v63, v63 quad_perm:[2,3,0,1] row_mask:0xf bank_mask:0xf bound_ctrl:1
	v_pk_fma_f32 v[56:57], v[68:69], v[94:95], v[56:57] op_sel:[0,1,0] op_sel_hi:[1,1,1]
	v_add_f32_dpp v62, v62, v62 row_half_mirror row_mask:0xf bank_mask:0xf bound_ctrl:1
	v_add_f32_dpp v63, v63, v63 row_half_mirror row_mask:0xf bank_mask:0xf bound_ctrl:1
	v_pk_fma_f32 v[58:59], v[68:69], v[96:97], v[58:59] op_sel_hi:[1,0,1]
	v_add_f32_dpp v62, v62, v62 row_mirror row_mask:0xf bank_mask:0xf bound_ctrl:1
	v_add_f32_dpp v63, v63, v63 row_mirror row_mask:0xf bank_mask:0xf bound_ctrl:1
	v_pk_fma_f32 v[60:61], v[68:69], v[96:97], v[60:61] op_sel:[0,1,0] op_sel_hi:[1,1,1]
	v_pk_fma_f32 v[72:73], v[62:63], v[98:99], v[54:55] op_sel_hi:[1,0,1]
	v_pk_fma_f32 v[74:75], v[62:63], v[98:99], v[56:57] op_sel:[0,1,0] op_sel_hi:[1,1,1]
	v_pk_fma_f32 v[76:77], v[62:63], v[100:101], v[58:59] op_sel_hi:[1,0,1]
	v_pk_fma_f32 v[78:79], v[62:63], v[100:101], v[60:61] op_sel:[0,1,0] op_sel_hi:[1,1,1]
	ds_read_b128 v[86:89], v80 offset:6656
	ds_read_b128 v[90:93], v80 offset:2560
	ds_read_b128 v[94:97], v80 offset:14848
	ds_read_b64 v[68:69], v81 offset:1280
	ds_read_b128 v[98:101], v80 offset:10752
	s_waitcnt lgkmcnt(7)
	v_pk_mul_f32 v[62:63], v[72:73], v[108:109] op_sel_hi:[1,0]
	v_pk_mul_f32 v[64:65], v[72:73], v[102:103] op_sel_hi:[1,0]
	v_pk_mul_f32 v[54:55], v[72:73], v[112:113] op_sel_hi:[1,0]
	v_pk_fma_f32 v[62:63], v[74:75], v[108:109], v[62:63] op_sel:[0,1,0] op_sel_hi:[1,1,1]
	v_pk_fma_f32 v[64:65], v[74:75], v[102:103], v[64:65] op_sel:[0,1,0] op_sel_hi:[1,1,1]
	v_pk_mul_f32 v[56:57], v[74:75], v[112:113] op_sel:[0,1] op_sel_hi:[1,1]
	v_pk_fma_f32 v[62:63], v[76:77], v[110:111], v[62:63] op_sel_hi:[1,0,1]
	v_pk_fma_f32 v[64:65], v[76:77], v[104:105], v[64:65] op_sel_hi:[1,0,1]
	v_pk_mul_f32 v[58:59], v[76:77], v[114:115] op_sel_hi:[1,0]
	v_pk_fma_f32 v[62:63], v[78:79], v[110:111], v[62:63] op_sel:[0,1,0] op_sel_hi:[1,1,1]
	v_pk_fma_f32 v[64:65], v[78:79], v[104:105], v[64:65] op_sel:[0,1,0] op_sel_hi:[1,1,1]
	v_pk_mul_f32 v[60:61], v[78:79], v[114:115] op_sel:[0,1] op_sel_hi:[1,1]
	ds_write_b64 v82, v[64:65] offset:18432
	ds_read_b128 v[102:105], v80 offset:18944
	v_add_f32_dpp v62, v62, v62 quad_perm:[1,0,3,2] row_mask:0xf bank_mask:0xf bound_ctrl:1
	v_add_f32_dpp v63, v63, v63 quad_perm:[1,0,3,2] row_mask:0xf bank_mask:0xf bound_ctrl:1
	v_pk_fma_f32 v[54:55], v[66:67], v[116:117], v[54:55] op_sel_hi:[1,0,1]
	v_add_f32_dpp v62, v62, v62 quad_perm:[2,3,0,1] row_mask:0xf bank_mask:0xf bound_ctrl:1
	v_add_f32_dpp v63, v63, v63 quad_perm:[2,3,0,1] row_mask:0xf bank_mask:0xf bound_ctrl:1
	v_pk_fma_f32 v[56:57], v[66:67], v[116:117], v[56:57] op_sel:[0,1,0] op_sel_hi:[1,1,1]
	v_add_f32_dpp v62, v62, v62 row_half_mirror row_mask:0xf bank_mask:0xf bound_ctrl:1
	v_add_f32_dpp v63, v63, v63 row_half_mirror row_mask:0xf bank_mask:0xf bound_ctrl:1
	v_pk_fma_f32 v[58:59], v[66:67], v[118:119], v[58:59] op_sel_hi:[1,0,1]
	v_add_f32_dpp v62, v62, v62 row_mirror row_mask:0xf bank_mask:0xf bound_ctrl:1
	v_add_f32_dpp v63, v63, v63 row_mirror row_mask:0xf bank_mask:0xf bound_ctrl:1
	v_pk_fma_f32 v[60:61], v[66:67], v[118:119], v[60:61] op_sel:[0,1,0] op_sel_hi:[1,1,1]
	v_pk_fma_f32 v[72:73], v[62:63], v[120:121], v[54:55] op_sel_hi:[1,0,1]
	v_pk_fma_f32 v[74:75], v[62:63], v[120:121], v[56:57] op_sel:[0,1,0] op_sel_hi:[1,1,1]
	v_pk_fma_f32 v[76:77], v[62:63], v[122:123], v[58:59] op_sel_hi:[1,0,1]
	v_pk_fma_f32 v[78:79], v[62:63], v[122:123], v[60:61] op_sel:[0,1,0] op_sel_hi:[1,1,1]
	ds_read_b128 v[108:111], v80 offset:6912
	ds_read_b128 v[112:115], v80 offset:2816
	ds_read_b128 v[116:119], v80 offset:15104
	ds_read_b64 v[66:67], v81 offset:1408
	ds_read_b128 v[120:123], v80 offset:11008
	s_waitcnt lgkmcnt(7)
; #define SC_LD(W, A, Bv, K, R, V, s_) do { const float* p_ = B_ + (s_) * 64 + kl * 4; W = *(const f32x4*)p_; A = *(const f32x4*)(p_ + 2048); Bv = *(const f32x4*)(p_ + 4096); K = *(const f32x4*)(p_ + 6144); R = *(const f32x4*)(p_ + 8192); V = B_[10240 + (s_) * 32 + row]; } while (0)
; #define SC_STEP(W, A, Bv, K, R, V, s_) do { float sa_ = S.x * A.x; sa_ = fmaf(S.y, A.y, sa_); sa_ = fmaf(S.z, A.z, sa_); sa_ = fmaf(S.w, A.w, sa_); \
;                     sa_ = row16_sum(sa_); S = S * W + Bv * sa_ + K * V; \
;                     float y_ = S.x * R.x; y_ = fmaf(S.y, R.y, y_); y_ = fmaf(S.z, R.z, y_); y_ = fmaf(S.w, R.w, y_); yp[((s_) * 32 + row) * 20 + kl] = y_; } while (0)
; __global__ void __launch_bounds__(NT, 2) mk_fwd(Args args) {
;     ...
;                 f32x4 w0, a0, b0, k0, r0, w1, a1, b1, k1, r1; float v0, v1;
;                 SC_LD(w0, a0, b0, k0, r0, v0, 0);
; #pragma unroll
;                 for (int s = 0; s < TC; s += 2) {
;                     SC_LD(w1, a1, b1, k1, r1, v1, s + 1);
;                     SC_STEP(w0, a0, b0, k0, r0, v0, s);
;                     if (s + 2 < TC) SC_LD(w0, a0, b0, k0, r0, v0, s + 2);
;                     SC_STEP(w1, a1, b1, k1, r1, v1, s + 1);
	v_pk_mul_f32 v[62:63], v[72:73], v[86:87] op_sel_hi:[1,0]
	v_pk_mul_f32 v[64:65], v[72:73], v[124:125] op_sel_hi:[1,0]
	v_pk_mul_f32 v[54:55], v[72:73], v[90:91] op_sel_hi:[1,0]
	v_pk_fma_f32 v[62:63], v[74:75], v[86:87], v[62:63] op_sel:[0,1,0] op_sel_hi:[1,1,1]
	v_pk_fma_f32 v[64:65], v[74:75], v[124:125], v[64:65] op_sel:[0,1,0] op_sel_hi:[1,1,1]
	v_pk_mul_f32 v[56:57], v[74:75], v[90:91] op_sel:[0,1] op_sel_hi:[1,1]
	v_pk_fma_f32 v[62:63], v[76:77], v[88:89], v[62:63] op_sel_hi:[1,0,1]
	v_pk_fma_f32 v[64:65], v[76:77], v[126:127], v[64:65] op_sel_hi:[1,0,1]
	v_pk_mul_f32 v[58:59], v[76:77], v[92:93] op_sel_hi:[1,0]
	v_pk_fma_f32 v[62:63], v[78:79], v[88:89], v[62:63] op_sel:[0,1,0] op_sel_hi:[1,1,1]
	v_pk_fma_f32 v[64:65], v[78:79], v[126:127], v[64:65] op_sel:[0,1,0] op_sel_hi:[1,1,1]
	v_pk_mul_f32 v[60:61], v[78:79], v[92:93] op_sel:[0,1] op_sel_hi:[1,1]
	ds_write_b64 v82, v[64:65] offset:20736
	ds_read_b128 v[124:127], v80 offset:19200
	v_add_f32_dpp v62, v62, v62 quad_perm:[1,0,3,2] row_mask:0xf bank_mask:0xf bound_ctrl:1
	v_add_f32_dpp v63, v63, v63 quad_perm:[1,0,3,2] row_mask:0xf bank_mask:0xf bound_ctrl:1
	v_pk_fma_f32 v[54:55], v[68:69], v[94:95], v[54:55] op_sel_hi:[1,0,1]
	v_add_f32_dpp v62, v62, v62 quad_perm:[2,3,0,1] row_mask:0xf bank_mask:0xf bound_ctrl:1
	v_add_f32_dpp v63, v63, v63 quad_perm:[2,3,0,1] row_mask:0xf bank_mask:0xf bound_ctrl:1
	v_pk_fma_f32 v[56:57], v[68:69], v[94:95], v[56:57] op_sel:[0,1,0] op_sel_hi:[1,1,1]
	v_add_f32_dpp v62, v62, v62 row_half_mirror row_mask:0xf bank_mask:0xf bound_ctrl:1
	v_add_f32_dpp v63, v63, v63 row_half_mirror row_mask:0xf bank_mask:0xf bound_ctrl:1
	v_pk_fma_f32 v[58:59], v[68:69], v[96:97], v[58:59] op_sel_hi:[1,0,1]
	v_add_f32_dpp v62, v62, v62 row_mirror row_mask:0xf bank_mask:0xf bound_ctrl:1
	v_add_f32_dpp v63, v63, v63 row_mirror row_mask:0xf bank_mask:0xf bound_ctrl:1
	v_pk_fma_f32 v[60:61], v[68:69], v[96:97], v[60:61] op_sel:[0,1,0] op_sel_hi:[1,1,1]
	v_pk_fma_f32 v[72:73], v[62:63], v[98:99], v[54:55] op_sel_hi:[1,0,1]
	v_pk_fma_f32 v[74:75], v[62:63], v[98:99], v[56:57] op_sel:[0,1,0] op_sel_hi:[1,1,1]
	v_pk_fma_f32 v[76:77], v[62:63], v[100:101], v[58:59] op_sel_hi:[1,0,1]
	v_pk_fma_f32 v[78:79], v[62:63], v[100:101], v[60:61] op_sel:[0,1,0] op_sel_hi:[1,1,1]
	ds_read_b128 v[86:89], v80 offset:7168
	ds_read_b128 v[90:93], v80 offset:3072
	ds_read_b128 v[94:97], v80 offset:15360
	ds_read_b64 v[68:69], v81 offset:1536
	ds_read_b128 v[98:101], v80 offset:11264
	s_waitcnt lgkmcnt(7)
	v_pk_mul_f32 v[62:63], v[72:73], v[108:109] op_sel_hi:[1,0]
	v_pk_mul_f32 v[64:65], v[72:73], v[102:103] op_sel_hi:[1,0]
	v_pk_mul_f32 v[54:55], v[72:73], v[112:113] op_sel_hi:[1,0]
	v_pk_fma_f32 v[62:63], v[74:75], v[108:109], v[62:63] op_sel:[0,1,0] op_sel_hi:[1,1,1]
	v_pk_fma_f32 v[64:65], v[74:75], v[102:103], v[64:65] op_sel:[0,1,0] op_sel_hi:[1,1,1]
	v_pk_mul_f32 v[56:57], v[74:75], v[112:113] op_sel:[0,1] op_sel_hi:[1,1]
	v_pk_fma_f32 v[62:63], v[76:77], v[110:111], v[62:63] op_sel_hi:[1,0,1]
	v_pk_fma_f32 v[64:65], v[76:77], v[104:105], v[64:65] op_sel_hi:[1,0,1]
	v_pk_mul_f32 v[58:59], v[76:77], v[114:115] op_sel_hi:[1,0]
	v_pk_fma_f32 v[62:63], v[78:79], v[110:111], v[62:63] op_sel:[0,1,0] op_sel_hi:[1,1,1]
	v_pk_fma_f32 v[64:65], v[78:79], v[104:105], v[64:65] op_sel:[0,1,0] op_sel_hi:[1,1,1]
	v_pk_mul_f32 v[60:61], v[78:79], v[114:115] op_sel:[0,1] op_sel_hi:[1,1]
	ds_write_b64 v82, v[64:65] offset:23040
	ds_read_b128 v[102:105], v80 offset:19456
	v_add_f32_dpp v62, v62, v62 quad_perm:[1,0,3,2] row_mask:0xf bank_mask:0xf bound_ctrl:1
	v_add_f32_dpp v63, v63, v63 quad_perm:[1,0,3,2] row_mask:0xf bank_mask:0xf bound_ctrl:1
	v_pk_fma_f32 v[54:55], v[66:67], v[116:117], v[54:55] op_sel_hi:[1,0,1]
	v_add_f32_dpp v62, v62, v62 quad_perm:[2,3,0,1] row_mask:0xf bank_mask:0xf bound_ctrl:1
	v_add_f32_dpp v63, v63, v63 quad_perm:[2,3,0,1] row_mask:0xf bank_mask:0xf bound_ctrl:1
	v_pk_fma_f32 v[56:57], v[66:67], v[116:117], v[56:57] op_sel:[0,1,0] op_sel_hi:[1,1,1]
	v_add_f32_dpp v62, v62, v62 row_half_mirror row_mask:0xf bank_mask:0xf bound_ctrl:1
	v_add_f32_dpp v63, v63, v63 row_half_mirror row_mask:0xf bank_mask:0xf bound_ctrl:1
	v_pk_fma_f32 v[58:59], v[66:67], v[118:119], v[58:59] op_sel_hi:[1,0,1]
	v_add_f32_dpp v62, v62, v62 row_mirror row_mask:0xf bank_mask:0xf bound_ctrl:1
	v_add_f32_dpp v63, v63, v63 row_mirror row_mask:0xf bank_mask:0xf bound_ctrl:1
	v_pk_fma_f32 v[60:61], v[66:67], v[118:119], v[60:61] op_sel:[0,1,0] op_sel_hi:[1,1,1]
	v_pk_fma_f32 v[72:73], v[62:63], v[120:121], v[54:55] op_sel_hi:[1,0,1]
	v_pk_fma_f32 v[74:75], v[62:63], v[120:121], v[56:57] op_sel:[0,1,0] op_sel_hi:[1,1,1]
	v_pk_fma_f32 v[76:77], v[62:63], v[122:123], v[58:59] op_sel_hi:[1,0,1]
	v_pk_fma_f32 v[78:79], v[62:63], v[122:123], v[60:61] op_sel:[0,1,0] op_sel_hi:[1,1,1]
	ds_read_b128 v[108:111], v80 offset:7424
	ds_read_b128 v[112:115], v80 offset:3328
	ds_read_b128 v[116:119], v80 offset:15616
	ds_read_b64 v[66:67], v81 offset:1664
	ds_read_b128 v[120:123], v80 offset:11520
	s_waitcnt lgkmcnt(7)
; #define SC_LD(W, A, Bv, K, R, V, s_) do { const float* p_ = B_ + (s_) * 64 + kl * 4; W = *(const f32x4*)p_; A = *(const f32x4*)(p_ + 2048); Bv = *(const f32x4*)(p_ + 4096); K = *(const f32x4*)(p_ + 6144); R = *(const f32x4*)(p_ + 8192); V = B_[10240 + (s_) * 32 + row]; } while (0)
; #define SC_STEP(W, A, Bv, K, R, V, s_) do { float sa_ = S.x * A.x; sa_ = fmaf(S.y, A.y, sa_); sa_ = fmaf(S.z, A.z, sa_); sa_ = fmaf(S.w, A.w, sa_); \
;                     sa_ = row16_sum(sa_); S = S * W + Bv * sa_ + K * V; \
;                     float y_ = S.x * R.x; y_ = fmaf(S.y, R.y, y_); y_ = fmaf(S.z, R.z, y_); y_ = fmaf(S.w, R.w, y_); yp[((s_) * 32 + row) * 20 + kl] = y_; } while (0)
; __global__ void __launch_bounds__(NT, 2) mk_fwd(Args args) {
;     ...
;                 f32x4 w0, a0, b0, k0, r0, w1, a1, b1, k1, r1; float v0, v1;
;                 SC_LD(w0, a0, b0, k0, r0, v0, 0);
; #pragma unroll
;                 for (int s = 0; s < TC; s += 2) {
;                     SC_LD(w1, a1, b1, k1, r1, v1, s + 1);
;                     SC_STEP(w0, a0, b0, k0, r0, v0, s);
;                     if (s + 2 < TC) SC_LD(w0, a0, b0, k0, r0, v0, s + 2);
;                     SC_STEP(w1, a1, b1, k1, r1, v1, s + 1);
	v_pk_mul_f32 v[62:63], v[72:73], v[86:87] op_sel_hi:[1,0]
	v_pk_mul_f32 v[64:65], v[72:73], v[124:125] op_sel_hi:[1,0]
	v_pk_mul_f32 v[54:55], v[72:73], v[90:91] op_sel_hi:[1,0]
	v_pk_fma_f32 v[62:63], v[74:75], v[86:87], v[62:63] op_sel:[0,1,0] op_sel_hi:[1,1,1]
	v_pk_fma_f32 v[64:65], v[74:75], v[124:125], v[64:65] op_sel:[0,1,0] op_sel_hi:[1,1,1]
	v_pk_mul_f32 v[56:57], v[74:75], v[90:91] op_sel:[0,1] op_sel_hi:[1,1]
	v_pk_fma_f32 v[62:63], v[76:77], v[88:89], v[62:63] op_sel_hi:[1,0,1]
	v_pk_fma_f32 v[64:65], v[76:77], v[126:127], v[64:65] op_sel_hi:[1,0,1]
	v_pk_mul_f32 v[58:59], v[76:77], v[92:93] op_sel_hi:[1,0]
	v_pk_fma_f32 v[62:63], v[78:79], v[88:89], v[62:63] op_sel:[0,1,0] op_sel_hi:[1,1,1]
	v_pk_fma_f32 v[64:65], v[78:79], v[126:127], v[64:65] op_sel:[0,1,0] op_sel_hi:[1,1,1]
	v_pk_mul_f32 v[60:61], v[78:79], v[92:93] op_sel:[0,1] op_sel_hi:[1,1]
	ds_write_b64 v82, v[64:65] offset:25344
	ds_read_b128 v[124:127], v80 offset:19712
	v_add_f32_dpp v62, v62, v62 quad_perm:[1,0,3,2] row_mask:0xf bank_mask:0xf bound_ctrl:1
	v_add_f32_dpp v63, v63, v63 quad_perm:[1,0,3,2] row_mask:0xf bank_mask:0xf bound_ctrl:1
	v_pk_fma_f32 v[54:55], v[68:69], v[94:95], v[54:55] op_sel_hi:[1,0,1]
	v_add_f32_dpp v62, v62, v62 quad_perm:[2,3,0,1] row_mask:0xf bank_mask:0xf bound_ctrl:1
	v_add_f32_dpp v63, v63, v63 quad_perm:[2,3,0,1] row_mask:0xf bank_mask:0xf bound_ctrl:1
	v_pk_fma_f32 v[56:57], v[68:69], v[94:95], v[56:57] op_sel:[0,1,0] op_sel_hi:[1,1,1]
	v_add_f32_dpp v62, v62, v62 row_half_mirror row_mask:0xf bank_mask:0xf bound_ctrl:1
	v_add_f32_dpp v63, v63, v63 row_half_mirror row_mask:0xf bank_mask:0xf bound_ctrl:1
	v_pk_fma_f32 v[58:59], v[68:69], v[96:97], v[58:59] op_sel_hi:[1,0,1]
	v_add_f32_dpp v62, v62, v62 row_mirror row_mask:0xf bank_mask:0xf bound_ctrl:1
	v_add_f32_dpp v63, v63, v63 row_mirror row_mask:0xf bank_mask:0xf bound_ctrl:1
	v_pk_fma_f32 v[60:61], v[68:69], v[96:97], v[60:61] op_sel:[0,1,0] op_sel_hi:[1,1,1]
	v_pk_fma_f32 v[72:73], v[62:63], v[98:99], v[54:55] op_sel_hi:[1,0,1]
	v_pk_fma_f32 v[74:75], v[62:63], v[98:99], v[56:57] op_sel:[0,1,0] op_sel_hi:[1,1,1]
	v_pk_fma_f32 v[76:77], v[62:63], v[100:101], v[58:59] op_sel_hi:[1,0,1]
	v_pk_fma_f32 v[78:79], v[62:63], v[100:101], v[60:61] op_sel:[0,1,0] op_sel_hi:[1,1,1]
	ds_read_b128 v[86:89], v80 offset:7680
	ds_read_b128 v[90:93], v80 offset:3584
	ds_read_b128 v[94:97], v80 offset:15872
	ds_read_b64 v[68:69], v81 offset:1792
	ds_read_b128 v[98:101], v80 offset:11776
	s_waitcnt lgkmcnt(7)
	v_pk_mul_f32 v[62:63], v[72:73], v[108:109] op_sel_hi:[1,0]
	v_pk_mul_f32 v[64:65], v[72:73], v[102:103] op_sel_hi:[1,0]
	v_pk_mul_f32 v[54:55], v[72:73], v[112:113] op_sel_hi:[1,0]
	v_pk_fma_f32 v[62:63], v[74:75], v[108:109], v[62:63] op_sel:[0,1,0] op_sel_hi:[1,1,1]
	v_pk_fma_f32 v[64:65], v[74:75], v[102:103], v[64:65] op_sel:[0,1,0] op_sel_hi:[1,1,1]
	v_pk_mul_f32 v[56:57], v[74:75], v[112:113] op_sel:[0,1] op_sel_hi:[1,1]
	v_pk_fma_f32 v[62:63], v[76:77], v[110:111], v[62:63] op_sel_hi:[1,0,1]
	v_pk_fma_f32 v[64:65], v[76:77], v[104:105], v[64:65] op_sel_hi:[1,0,1]
	v_pk_mul_f32 v[58:59], v[76:77], v[114:115] op_sel_hi:[1,0]
	v_pk_fma_f32 v[62:63], v[78:79], v[110:111], v[62:63] op_sel:[0,1,0] op_sel_hi:[1,1,1]
	v_pk_fma_f32 v[64:65], v[78:79], v[104:105], v[64:65] op_sel:[0,1,0] op_sel_hi:[1,1,1]
	v_pk_mul_f32 v[60:61], v[78:79], v[114:115] op_sel:[0,1] op_sel_hi:[1,1]
	ds_write_b64 v82, v[64:65] offset:27648
	ds_read_b128 v[102:105], v80 offset:19968
	v_add_f32_dpp v62, v62, v62 quad_perm:[1,0,3,2] row_mask:0xf bank_mask:0xf bound_ctrl:1
	v_add_f32_dpp v63, v63, v63 quad_perm:[1,0,3,2] row_mask:0xf bank_mask:0xf bound_ctrl:1
	v_pk_fma_f32 v[54:55], v[66:67], v[116:117], v[54:55] op_sel_hi:[1,0,1]
	v_add_f32_dpp v62, v62, v62 quad_perm:[2,3,0,1] row_mask:0xf bank_mask:0xf bound_ctrl:1
	v_add_f32_dpp v63, v63, v63 quad_perm:[2,3,0,1] row_mask:0xf bank_mask:0xf bound_ctrl:1
	v_pk_fma_f32 v[56:57], v[66:67], v[116:117], v[56:57] op_sel:[0,1,0] op_sel_hi:[1,1,1]
	v_add_f32_dpp v62, v62, v62 row_half_mirror row_mask:0xf bank_mask:0xf bound_ctrl:1
	v_add_f32_dpp v63, v63, v63 row_half_mirror row_mask:0xf bank_mask:0xf bound_ctrl:1
	v_pk_fma_f32 v[58:59], v[66:67], v[118:119], v[58:59] op_sel_hi:[1,0,1]
	v_add_f32_dpp v62, v62, v62 row_mirror row_mask:0xf bank_mask:0xf bound_ctrl:1
	v_add_f32_dpp v63, v63, v63 row_mirror row_mask:0xf bank_mask:0xf bound_ctrl:1
	v_pk_fma_f32 v[60:61], v[66:67], v[118:119], v[60:61] op_sel:[0,1,0] op_sel_hi:[1,1,1]
	v_pk_fma_f32 v[72:73], v[62:63], v[120:121], v[54:55] op_sel_hi:[1,0,1]
	v_pk_fma_f32 v[74:75], v[62:63], v[120:121], v[56:57] op_sel:[0,1,0] op_sel_hi:[1,1,1]
	v_pk_fma_f32 v[76:77], v[62:63], v[122:123], v[58:59] op_sel_hi:[1,0,1]
	v_pk_fma_f32 v[78:79], v[62:63], v[122:123], v[60:61] op_sel:[0,1,0] op_sel_hi:[1,1,1]
	ds_read_b128 v[108:111], v80 offset:7936
	ds_read_b128 v[112:115], v80 offset:3840
	ds_read_b128 v[116:119], v80 offset:16128
	ds_read_b64 v[66:67], v81 offset:1920
	ds_read_b128 v[120:123], v80 offset:12032
	s_waitcnt lgkmcnt(7)
; #define LDS_BARRIER() do { asm volatile("s_waitcnt lgkmcnt(0)" ::: "memory"); __builtin_amdgcn_s_barrier(); asm volatile("" ::: "memory"); } while (0)
; #define SC_LD(W, A, Bv, K, R, V, s_) do { const float* p_ = B_ + (s_) * 64 + kl * 4; W = *(const f32x4*)p_; A = *(const f32x4*)(p_ + 2048); Bv = *(const f32x4*)(p_ + 4096); K = *(const f32x4*)(p_ + 6144); R = *(const f32x4*)(p_ + 8192); V = B_[10240 + (s_) * 32 + row]; } while (0)
; #define SC_STEP(W, A, Bv, K, R, V, s_) do { float sa_ = S.x * A.x; sa_ = fmaf(S.y, A.y, sa_); sa_ = fmaf(S.z, A.z, sa_); sa_ = fmaf(S.w, A.w, sa_); \
;                     sa_ = row16_sum(sa_); S = S * W + Bv * sa_ + K * V; \
;                     float y_ = S.x * R.x; y_ = fmaf(S.y, R.y, y_); y_ = fmaf(S.z, R.z, y_); y_ = fmaf(S.w, R.w, y_); yp[((s_) * 32 + row) * 20 + kl] = y_; } while (0)
; __global__ void __launch_bounds__(NT, 2) mk_fwd(Args args) {
;     ...
;                 f32x4 w0, a0, b0, k0, r0, w1, a1, b1, k1, r1; float v0, v1;
;                 SC_LD(w0, a0, b0, k0, r0, v0, 0);
; #pragma unroll
;                 for (int s = 0; s < TC; s += 2) {
;                     SC_LD(w1, a1, b1, k1, r1, v1, s + 1);
;                     SC_STEP(w0, a0, b0, k0, r0, v0, s);
;                     if (s + 2 < TC) SC_LD(w0, a0, b0, k0, r0, v0, s + 2);
;                     SC_STEP(w1, a1, b1, k1, r1, v1, s + 1);
;                 }
;     ...
;                 LDS_BARRIER();
; #pragma unroll
;                 for (int o2 = 0; o2 < 2; ++o2) {
;                     const int oi = tid + o2 * NT; const float* pp = yp + oi * 20; const f32x4 p0 = *(const f32x4*)pp, p1 = *(const f32x4*)(pp + 4), p2 = *(const f32x4*)(pp + 8), p3 = *(const f32x4*)(pp + 12);
;                     const f32x4 t = (p0 + p1) + (p2 + p3);
;                     Y[((size_t)b * SEQ + c * TC + (oi >> 5)) * 1024 + h * 64 + half * 32 + (oi & 31)] = (t.x + t.y) + (t.z + t.w); }
;                 if (c + 1 < SEQ / TC) SC_STORE();
;                 LDS_BARRIER();
	v_pk_mul_f32 v[62:63], v[72:73], v[86:87] op_sel_hi:[1,0]
	v_pk_mul_f32 v[64:65], v[72:73], v[124:125] op_sel_hi:[1,0]
	v_pk_mul_f32 v[54:55], v[72:73], v[90:91] op_sel_hi:[1,0]
	v_pk_fma_f32 v[62:63], v[74:75], v[86:87], v[62:63] op_sel:[0,1,0] op_sel_hi:[1,1,1]
	v_pk_fma_f32 v[64:65], v[74:75], v[124:125], v[64:65] op_sel:[0,1,0] op_sel_hi:[1,1,1]
	v_pk_mul_f32 v[56:57], v[74:75], v[90:91] op_sel:[0,1] op_sel_hi:[1,1]
	v_pk_fma_f32 v[62:63], v[76:77], v[88:89], v[62:63] op_sel_hi:[1,0,1]
	v_pk_fma_f32 v[64:65], v[76:77], v[126:127], v[64:65] op_sel_hi:[1,0,1]
	v_pk_mul_f32 v[58:59], v[76:77], v[92:93] op_sel_hi:[1,0]
	v_pk_fma_f32 v[62:63], v[78:79], v[88:89], v[62:63] op_sel:[0,1,0] op_sel_hi:[1,1,1]
	v_pk_fma_f32 v[64:65], v[78:79], v[126:127], v[64:65] op_sel:[0,1,0] op_sel_hi:[1,1,1]
	v_pk_mul_f32 v[60:61], v[78:79], v[92:93] op_sel:[0,1] op_sel_hi:[1,1]
	ds_write_b64 v82, v[64:65] offset:29952
	ds_read_b128 v[124:127], v80 offset:20224
	v_add_f32_dpp v62, v62, v62 quad_perm:[1,0,3,2] row_mask:0xf bank_mask:0xf bound_ctrl:1
	v_add_f32_dpp v63, v63, v63 quad_perm:[1,0,3,2] row_mask:0xf bank_mask:0xf bound_ctrl:1
	v_pk_fma_f32 v[54:55], v[68:69], v[94:95], v[54:55] op_sel_hi:[1,0,1]
	v_add_f32_dpp v62, v62, v62 quad_perm:[2,3,0,1] row_mask:0xf bank_mask:0xf bound_ctrl:1
	v_add_f32_dpp v63, v63, v63 quad_perm:[2,3,0,1] row_mask:0xf bank_mask:0xf bound_ctrl:1
	v_pk_fma_f32 v[56:57], v[68:69], v[94:95], v[56:57] op_sel:[0,1,0] op_sel_hi:[1,1,1]
	v_add_f32_dpp v62, v62, v62 row_half_mirror row_mask:0xf bank_mask:0xf bound_ctrl:1
	v_add_f32_dpp v63, v63, v63 row_half_mirror row_mask:0xf bank_mask:0xf bound_ctrl:1
	v_pk_fma_f32 v[58:59], v[68:69], v[96:97], v[58:59] op_sel_hi:[1,0,1]
	v_add_f32_dpp v62, v62, v62 row_mirror row_mask:0xf bank_mask:0xf bound_ctrl:1
	v_add_f32_dpp v63, v63, v63 row_mirror row_mask:0xf bank_mask:0xf bound_ctrl:1
	v_pk_fma_f32 v[60:61], v[68:69], v[96:97], v[60:61] op_sel:[0,1,0] op_sel_hi:[1,1,1]
	v_pk_fma_f32 v[72:73], v[62:63], v[98:99], v[54:55] op_sel_hi:[1,0,1]
	v_pk_fma_f32 v[74:75], v[62:63], v[98:99], v[56:57] op_sel:[0,1,0] op_sel_hi:[1,1,1]
	v_pk_fma_f32 v[76:77], v[62:63], v[100:101], v[58:59] op_sel_hi:[1,0,1]
	v_pk_fma_f32 v[78:79], v[62:63], v[100:101], v[60:61] op_sel:[0,1,0] op_sel_hi:[1,1,1]
	s_waitcnt lgkmcnt(2)
	v_pk_mul_f32 v[62:63], v[72:73], v[108:109] op_sel_hi:[1,0]
	v_pk_mul_f32 v[64:65], v[72:73], v[102:103] op_sel_hi:[1,0]
	v_pk_mul_f32 v[54:55], v[72:73], v[112:113] op_sel_hi:[1,0]
	v_pk_fma_f32 v[62:63], v[74:75], v[108:109], v[62:63] op_sel:[0,1,0] op_sel_hi:[1,1,1]
	v_pk_fma_f32 v[64:65], v[74:75], v[102:103], v[64:65] op_sel:[0,1,0] op_sel_hi:[1,1,1]
	v_pk_mul_f32 v[56:57], v[74:75], v[112:113] op_sel:[0,1] op_sel_hi:[1,1]
	v_pk_fma_f32 v[62:63], v[76:77], v[110:111], v[62:63] op_sel_hi:[1,0,1]
	v_pk_fma_f32 v[64:65], v[76:77], v[104:105], v[64:65] op_sel_hi:[1,0,1]
	v_pk_mul_f32 v[58:59], v[76:77], v[114:115] op_sel_hi:[1,0]
	v_pk_fma_f32 v[62:63], v[78:79], v[110:111], v[62:63] op_sel:[0,1,0] op_sel_hi:[1,1,1]
	v_pk_fma_f32 v[64:65], v[78:79], v[104:105], v[64:65] op_sel:[0,1,0] op_sel_hi:[1,1,1]
	v_pk_mul_f32 v[60:61], v[78:79], v[114:115] op_sel:[0,1] op_sel_hi:[1,1]
	ds_write_b64 v82, v[64:65] offset:32256
	v_add_f32_dpp v62, v62, v62 quad_perm:[1,0,3,2] row_mask:0xf bank_mask:0xf bound_ctrl:1
	v_add_f32_dpp v63, v63, v63 quad_perm:[1,0,3,2] row_mask:0xf bank_mask:0xf bound_ctrl:1
	v_pk_fma_f32 v[54:55], v[66:67], v[116:117], v[54:55] op_sel_hi:[1,0,1]
	v_add_f32_dpp v62, v62, v62 quad_perm:[2,3,0,1] row_mask:0xf bank_mask:0xf bound_ctrl:1
	v_add_f32_dpp v63, v63, v63 quad_perm:[2,3,0,1] row_mask:0xf bank_mask:0xf bound_ctrl:1
	v_pk_fma_f32 v[56:57], v[66:67], v[116:117], v[56:57] op_sel:[0,1,0] op_sel_hi:[1,1,1]
	v_add_f32_dpp v62, v62, v62 row_half_mirror row_mask:0xf bank_mask:0xf bound_ctrl:1
	v_add_f32_dpp v63, v63, v63 row_half_mirror row_mask:0xf bank_mask:0xf bound_ctrl:1
	v_pk_fma_f32 v[58:59], v[66:67], v[118:119], v[58:59] op_sel_hi:[1,0,1]
	v_add_f32_dpp v62, v62, v62 row_mirror row_mask:0xf bank_mask:0xf bound_ctrl:1
	v_add_f32_dpp v63, v63, v63 row_mirror row_mask:0xf bank_mask:0xf bound_ctrl:1
	v_pk_fma_f32 v[60:61], v[66:67], v[118:119], v[60:61] op_sel:[0,1,0] op_sel_hi:[1,1,1]
	v_pk_fma_f32 v[72:73], v[62:63], v[120:121], v[54:55] op_sel_hi:[1,0,1]
	v_pk_fma_f32 v[74:75], v[62:63], v[120:121], v[56:57] op_sel:[0,1,0] op_sel_hi:[1,1,1]
	v_pk_fma_f32 v[76:77], v[62:63], v[122:123], v[58:59] op_sel_hi:[1,0,1]
	v_pk_fma_f32 v[78:79], v[62:63], v[122:123], v[60:61] op_sel:[0,1,0] op_sel_hi:[1,1,1]
	s_waitcnt lgkmcnt(1)
	v_pk_mul_f32 v[64:65], v[72:73], v[124:125] op_sel_hi:[1,0]
	v_pk_fma_f32 v[64:65], v[74:75], v[124:125], v[64:65] op_sel:[0,1,0] op_sel_hi:[1,1,1]
	v_pk_fma_f32 v[64:65], v[76:77], v[126:127], v[64:65] op_sel_hi:[1,0,1]
	v_pk_fma_f32 v[64:65], v[78:79], v[126:127], v[64:65] op_sel:[0,1,0] op_sel_hi:[1,1,1]
	ds_write_b64 v82, v[64:65] offset:34560
	s_waitcnt lgkmcnt(0)
	s_barrier
	v_xor_b32_e32 v80, 0x5800, v80
	v_xor_b32_e32 v81, 0xf800, v81
	v_xor_b32_e32 v82, 0x1f000, v82
	s_sub_i32 s10, s10, 1
	s_cmp_lg_u32 s10, 0
	s_cbranch_scc1 .Lp4_cchunk
	s_branch .Lp4_taskend
; #define LDS_BARRIER() do { asm volatile("s_waitcnt lgkmcnt(0)" ::: "memory"); __builtin_amdgcn_s_barrier(); asm volatile("" ::: "memory"); } while (0)
; __global__ void __launch_bounds__(NT, 2) mk_fwd(Args args) {
;     ...
;         for (int task_ = bx; task_ < 256 * RMUL(4); task_ += G) {
;             const int tb_ = task_ & 255; const int task = ((tb_ >> 4) << 4) | ((tb_ & 7) << 1) | ((tb_ >> 3) & 1); const int bh = task >> 1, half = task & 1, b = bh >> 4, h = bh & 15;
;             const int stp = tid >> 4, q = tid & 15;
;             const size_t base = ((size_t)b * SEQ + stp) * 1024 + h * 64;
;             f32x4 ld_dec; u32x2 ld_kk, ld_bb, ld_kp, ld_rr; unsigned ld_vv;
;     ...
;             __syncthreads();
;             SC_LOAD(0); SC_STORE();
;             __syncthreads();
;             f32x4 S = (f32x4){0.f, 0.f, 0.f, 0.f};
;             const int row = wave * 4 + (lane >> 4), kl = lane & 15;
;             const float* B_ = (const float*)lds;
;             for (int c = 0; c < SEQ / TC; ++c) {
;                 if (c + 1 < SEQ / TC) SC_LOAD((c + 1) * TC);
;     ...
;                 f32x4 w0, a0, b0, k0, r0, w1, a1, b1, k1, r1; float v0, v1;
;                 SC_LD(w0, a0, b0, k0, r0, v0, 0);
; #pragma unroll
;                 for (int s = 0; s < TC; s += 2) {
;                     SC_LD(w1, a1, b1, k1, r1, v1, s + 1);
;                     SC_STEP(w0, a0, b0, k0, r0, v0, s);
;                     if (s + 2 < TC) SC_LD(w0, a0, b0, k0, r0, v0, s + 2);
;                     SC_STEP(w1, a1, b1, k1, r1, v1, s + 1);
;                 }
;     ...
;                 LDS_BARRIER();
; #pragma unroll
;                 for (int o2 = 0; o2 < 2; ++o2) {
;                     const int oi = tid + o2 * NT; const float* pp = yp + oi * 20; const f32x4 p0 = *(const f32x4*)pp, p1 = *(const f32x4*)(pp + 4), p2 = *(const f32x4*)(pp + 8), p3 = *(const f32x4*)(pp + 12);
;                     const f32x4 t = (p0 + p1) + (p2 + p3);
;                     Y[((size_t)b * SEQ + c * TC + (oi >> 5)) * 1024 + h * 64 + half * 32 + (oi & 31)] = (t.x + t.y) + (t.z + t.w); }
;                 if (c + 1 < SEQ / TC) SC_STORE();
;                 LDS_BARRIER();
;             }
;     ...
;         }
.Lp4_helper:
	v_subrev_u32_e32 v54, 0x100, v168
	v_lshrrev_b32_e32 v55, 4, v54
	v_and_b32_e32 v56, 15, v54
	v_lshlrev_b32_e32 v57, 12, v55
	v_lshl_add_u32 v57, v56, 4, v57
	v_lshlrev_b32_e32 v58, 11, v55
	v_lshl_add_u32 v59, v56, 2, v58
	v_lshl_add_u32 v58, v56, 3, v58
	v_lshlrev_b32_e32 v60, 8, v55
	v_lshl_add_u32 v60, v56, 4, v60
	v_lshlrev_b32_e32 v61, 7, v55
	v_lshl_add_u32 v61, v56, 3, v61
	v_add_u32_e32 v61, 0x5000, v61
	v_mul_u32_u24_e32 v62, 0x90, v54
	v_add_u32_e32 v62, 0x14000, v62
	v_lshlrev_b32_e32 v63, 12, v55
	v_lshl_add_u32 v63, v56, 3, v63
	v_lshlrev_b32_e32 v50, 1, v60
	v_add_u32_e32 v50, 0x5800, v50
	v_lshlrev_b32_e32 v51, 1, v61
	v_add_u32_e32 v51, 0x5800, v51
	v_lshlrev_b32_e32 v52, 1, v62
	v_add_u32_e32 v52, 0xffff7000, v52
	global_load_dwordx4 v[0:3], v57, s[38:39]
	global_load_dwordx2 v[4:5], v58, s[40:41]
	global_load_dwordx2 v[6:7], v58, s[42:43]
	global_load_dwordx2 v[8:9], v58, s[44:45]
	global_load_dwordx2 v[10:11], v58, s[46:47]
	global_load_dword v12, v59, s[52:53]
	v_add_u32_e32 v57, 0x10000, v57
	v_add_u32_e32 v58, 0x8000, v58
	v_add_u32_e32 v59, 0x8000, v59
	s_waitcnt vmcnt(0)
	ds_write_b128 v60, v[0:3]
	v_lshlrev_b32_e32 v16, 16, v4
	v_and_b32_e32 v17, 0xffff0000, v4
	v_lshlrev_b32_e32 v18, 16, v5
	v_and_b32_e32 v19, 0xffff0000, v5
	v_xor_b32_e32 v16, 0x80000000, v16
	v_xor_b32_e32 v17, 0x80000000, v17
	v_xor_b32_e32 v18, 0x80000000, v18
	v_xor_b32_e32 v19, 0x80000000, v19
	ds_write_b128 v60, v[16:19] offset:4096
	v_lshlrev_b32_e32 v20, 16, v6
	v_and_b32_e32 v21, 0xffff0000, v6
	v_lshlrev_b32_e32 v22, 16, v7
	v_and_b32_e32 v23, 0xffff0000, v7
	ds_write_b128 v60, v[20:23] offset:8192
	v_lshlrev_b32_e32 v24, 16, v8
	v_and_b32_e32 v25, 0xffff0000, v8
	v_lshlrev_b32_e32 v26, 16, v9
	v_and_b32_e32 v27, 0xffff0000, v9
	ds_write_b128 v60, v[24:27] offset:12288
	v_lshlrev_b32_e32 v28, 16, v10
	v_and_b32_e32 v29, 0xffff0000, v10
	v_lshlrev_b32_e32 v30, 16, v11
	v_and_b32_e32 v31, 0xffff0000, v11
	ds_write_b128 v60, v[28:31] offset:16384
	v_lshlrev_b32_e32 v14, 16, v12
	v_and_b32_e32 v15, 0xffff0000, v12
	ds_write_b64 v61, v[14:15]
	global_load_dwordx4 v[0:3], v57, s[38:39]
	global_load_dwordx2 v[4:5], v58, s[40:41]
	global_load_dwordx2 v[6:7], v58, s[42:43]
	global_load_dwordx2 v[8:9], v58, s[44:45]
	global_load_dwordx2 v[10:11], v58, s[46:47]
	global_load_dword v12, v59, s[52:53]
	v_add_u32_e32 v57, 0x10000, v57
	v_add_u32_e32 v58, 0x8000, v58
	v_add_u32_e32 v59, 0x8000, v59
	s_waitcnt lgkmcnt(0)
	s_barrier
	v_sub_u32_e32 v60, v50, v60
	v_sub_u32_e32 v61, v51, v61
	s_mov_b32 s10, 0
.Lp4_hround:
	s_cmp_lt_u32 s10, 0x7f
	s_cbranch_scc0 .Lp4_hnostage
	s_waitcnt vmcnt(0)
	ds_write_b128 v60, v[0:3]
	v_lshlrev_b32_e32 v16, 16, v4
	v_and_b32_e32 v17, 0xffff0000, v4
	v_lshlrev_b32_e32 v18, 16, v5
	v_and_b32_e32 v19, 0xffff0000, v5
	v_xor_b32_e32 v16, 0x80000000, v16
	v_xor_b32_e32 v17, 0x80000000, v17
	v_xor_b32_e32 v18, 0x80000000, v18
	v_xor_b32_e32 v19, 0x80000000, v19
	ds_write_b128 v60, v[16:19] offset:4096
	v_lshlrev_b32_e32 v20, 16, v6
	v_and_b32_e32 v21, 0xffff0000, v6
	v_lshlrev_b32_e32 v22, 16, v7
	v_and_b32_e32 v23, 0xffff0000, v7
	ds_write_b128 v60, v[20:23] offset:8192
	v_lshlrev_b32_e32 v24, 16, v8
	v_and_b32_e32 v25, 0xffff0000, v8
	v_lshlrev_b32_e32 v26, 16, v9
	v_and_b32_e32 v27, 0xffff0000, v9
	ds_write_b128 v60, v[24:27] offset:12288
	v_lshlrev_b32_e32 v28, 16, v10
	v_and_b32_e32 v29, 0xffff0000, v10
	v_lshlrev_b32_e32 v30, 16, v11
	v_and_b32_e32 v31, 0xffff0000, v11
	ds_write_b128 v60, v[28:31] offset:16384
	v_lshlrev_b32_e32 v14, 16, v12
	v_and_b32_e32 v15, 0xffff0000, v12
	ds_write_b64 v61, v[14:15]
	s_cmp_lt_u32 s10, 0x7e
	s_cbranch_scc0 .Lp4_hnostage
	global_load_dwordx4 v[0:3], v57, s[38:39]
	global_load_dwordx2 v[4:5], v58, s[40:41]
	global_load_dwordx2 v[6:7], v58, s[42:43]
	global_load_dwordx2 v[8:9], v58, s[44:45]
	global_load_dwordx2 v[10:11], v58, s[46:47]
	global_load_dword v12, v59, s[52:53]
	v_add_u32_e32 v57, 0x10000, v57
	v_add_u32_e32 v58, 0x8000, v58
	v_add_u32_e32 v59, 0x8000, v59
.Lp4_hnostage:
	s_cmp_eq_u32 s10, 0
	s_cbranch_scc1 .Lp4_hnored
	ds_read_b128 v[16:19], v62 offset:0
	ds_read_b128 v[20:23], v62 offset:16
	ds_read_b128 v[24:27], v62 offset:32
	ds_read_b128 v[28:31], v62 offset:48
	ds_read_b128 v[32:35], v62 offset:64
	ds_read_b128 v[36:39], v62 offset:80
	ds_read_b128 v[40:43], v62 offset:96
	ds_read_b128 v[44:47], v62 offset:112
	s_waitcnt lgkmcnt(6)
	v_pk_add_f32 v[16:17], v[16:17], v[20:21]
	v_pk_add_f32 v[18:19], v[18:19], v[22:23]
	s_waitcnt lgkmcnt(4)
	v_pk_add_f32 v[24:25], v[24:25], v[28:29]
	v_pk_add_f32 v[26:27], v[26:27], v[30:31]
	s_waitcnt lgkmcnt(2)
	v_pk_add_f32 v[32:33], v[32:33], v[36:37]
	v_pk_add_f32 v[34:35], v[34:35], v[38:39]
	s_waitcnt lgkmcnt(0)
	v_pk_add_f32 v[40:41], v[40:41], v[44:45]
	v_pk_add_f32 v[42:43], v[42:43], v[46:47]
	v_pk_add_f32 v[16:17], v[16:17], v[24:25]
	v_pk_add_f32 v[18:19], v[18:19], v[26:27]
	v_pk_add_f32 v[32:33], v[32:33], v[40:41]
	v_pk_add_f32 v[34:35], v[34:35], v[42:43]
	v_pk_add_f32 v[16:17], v[16:17], v[32:33]
	v_pk_add_f32 v[18:19], v[18:19], v[34:35]
	v_pk_add_f32 v[16:17], v[16:17], v[18:19]
	global_store_dwordx2 v63, v[16:17], s[54:55]
	v_add_u32_e32 v63, 0x10000, v63
.Lp4_hnored:
	s_waitcnt lgkmcnt(0)
	s_barrier
	v_sub_u32_e32 v60, v50, v60
	v_sub_u32_e32 v61, v51, v61
	v_sub_u32_e32 v62, v52, v62
	s_add_i32 s10, s10, 1
	s_cmp_lt_u32 s10, 0x80
	s_cbranch_scc1 .Lp4_hround
	ds_read_b128 v[16:19], v62 offset:0
	ds_read_b128 v[20:23], v62 offset:16
	ds_read_b128 v[24:27], v62 offset:32
	ds_read_b128 v[28:31], v62 offset:48
	ds_read_b128 v[32:35], v62 offset:64
	ds_read_b128 v[36:39], v62 offset:80
	ds_read_b128 v[40:43], v62 offset:96
	ds_read_b128 v[44:47], v62 offset:112
	s_waitcnt lgkmcnt(6)
	v_pk_add_f32 v[16:17], v[16:17], v[20:21]
	v_pk_add_f32 v[18:19], v[18:19], v[22:23]
	s_waitcnt lgkmcnt(4)
	v_pk_add_f32 v[24:25], v[24:25], v[28:29]
	v_pk_add_f32 v[26:27], v[26:27], v[30:31]
	s_waitcnt lgkmcnt(2)
	v_pk_add_f32 v[32:33], v[32:33], v[36:37]
	v_pk_add_f32 v[34:35], v[34:35], v[38:39]
	s_waitcnt lgkmcnt(0)
	v_pk_add_f32 v[40:41], v[40:41], v[44:45]
	v_pk_add_f32 v[42:43], v[42:43], v[46:47]
	v_pk_add_f32 v[16:17], v[16:17], v[24:25]
	v_pk_add_f32 v[18:19], v[18:19], v[26:27]
	v_pk_add_f32 v[32:33], v[32:33], v[40:41]
	v_pk_add_f32 v[34:35], v[34:35], v[42:43]
	v_pk_add_f32 v[16:17], v[16:17], v[32:33]
	v_pk_add_f32 v[18:19], v[18:19], v[34:35]
	v_pk_add_f32 v[16:17], v[16:17], v[18:19]
	global_store_dwordx2 v63, v[16:17], s[54:55]
	v_add_u32_e32 v63, 0x10000, v63
.Lp4_taskend:
	s_add_i32 s48, s48, s84
	s_cmpk_gt_i32 s48, 0xff
	s_cbranch_scc0 .Lp4_task
